# mLSTM unit epilogue: all gain/gate row loads batched ahead of rstd, counted waits, 16 stores at the end (was 12 serial load/drain/store rounds)
# speedup vs baseline: 1.0029x; 1.0029x over previous
; DI void mlstm_unit(const Args& a, LAS unsigned char* lds, int b, int h, int J) {
;     ...
;     den += __shfl_xor(den, 32);
;     const float inv = 1.f / fmaxf(fabsf(den), __expf(-mt));
;     float s1 = 0.f;
; #pragma unroll
;     for (int db = 0; db < 4; ++db)
; #pragma unroll
;         for (int reg = 0; reg < 16; ++reg) { O[db][reg] *= inv; s1 += O[db][reg]; }
;     s1 += __shfl_xor(s1, 32);
;     const float mu = s1 * (1.f / 128.f);
.LBB0_2119:
	v_and_b32_e32 v68, 64, v1
	v_xor_b32_e32 v2, 32, v1
	v_add_u32_e32 v68, 64, v68
	v_cmp_lt_i32_e32 vcc, v2, v68
	v_mul_f32_e32 v68, 0xbfb8aa3b, v157
	v_exp_f32_e32 v68, v68
	v_cndmask_b32_e32 v2, v1, v2, vcc
	v_lshlrev_b32_e32 v91, 2, v2
	ds_bpermute_b32 v2, v91, v167
	v_lshl_add_u64 v[80:81], s[8:9], 0, v[154:155]
	s_mov_b32 s17, s11
	v_lshl_add_u64 v[80:81], v[80:81], 0, s[16:17]
	s_waitcnt lgkmcnt(0)
	v_add_f32_e32 v2, v167, v2
	v_max_f32_e64 v2, |v2|, v68
	v_div_scale_f32 v68, s[0:1], v2, v2, 1.0
	v_rcp_f32_e32 v69, v68
	v_div_scale_f32 v70, vcc, 1.0, v2, 1.0
	s_lshl_b32 s0, s48, 2
	v_fma_f32 v71, -v68, v69, 1.0
	v_fmac_f32_e32 v69, v71, v69
	v_mul_f32_e32 v71, v70, v69
	v_fma_f32 v72, -v68, v71, v70
	v_fmac_f32_e32 v71, v72, v69
	v_fma_f32 v68, -v68, v71, v70
	v_div_fmas_f32 v68, v68, v69, v71
	v_div_fixup_f32 v70, v68, v2, 1.0
	v_pk_mul_f32 v[68:69], v[58:59], v[70:71] op_sel_hi:[1,0]
	v_pk_mul_f32 v[72:73], v[60:61], v[70:71] op_sel_hi:[1,0]
	v_pk_mul_f32 v[74:75], v[62:63], v[70:71] op_sel_hi:[1,0]
	v_pk_mul_f32 v[76:77], v[64:65], v[70:71] op_sel_hi:[1,0]
	v_pk_mul_f32 v[78:79], v[66:67], v[70:71] op_sel_hi:[1,0]
	v_lshlrev_b32_e32 v71, 2, v166
	v_pk_mul_f32 v[84:85], v[4:5], v[70:71] op_sel_hi:[1,0]
	v_pk_mul_f32 v[82:83], v[6:7], v[70:71] op_sel_hi:[1,0]
	v_add_f32_e32 v2, 0, v84
	v_add_f32_e32 v2, v85, v2
	v_add_f32_e32 v2, v82, v2
	v_add_f32_e32 v2, v83, v2
	v_pk_mul_f32 v[84:85], v[8:9], v[70:71] op_sel_hi:[1,0]
	v_pk_mul_f32 v[82:83], v[10:11], v[70:71] op_sel_hi:[1,0]
	v_add_f32_e32 v2, v84, v2
	v_add_f32_e32 v2, v85, v2
	v_add_f32_e32 v2, v82, v2
	v_add_f32_e32 v2, v83, v2
	v_pk_mul_f32 v[84:85], v[12:13], v[70:71] op_sel_hi:[1,0]
	v_pk_mul_f32 v[82:83], v[14:15], v[70:71] op_sel_hi:[1,0]
	v_add_f32_e32 v2, v84, v2
	v_add_f32_e32 v2, v85, v2
	v_add_f32_e32 v2, v82, v2
	v_add_f32_e32 v2, v83, v2
	v_pk_mul_f32 v[84:85], v[16:17], v[70:71] op_sel_hi:[1,0]
	v_pk_mul_f32 v[82:83], v[18:19], v[70:71] op_sel_hi:[1,0]
	v_add_f32_e32 v2, v84, v2
	v_add_f32_e32 v2, v85, v2
	v_add_f32_e32 v2, v82, v2
	v_add_f32_e32 v2, v83, v2
	v_pk_mul_f32 v[84:85], v[20:21], v[70:71] op_sel_hi:[1,0]
	v_pk_mul_f32 v[82:83], v[22:23], v[70:71] op_sel_hi:[1,0]
	v_add_f32_e32 v2, v84, v2
	v_add_f32_e32 v2, v85, v2
	v_add_f32_e32 v2, v82, v2
	v_add_f32_e32 v2, v83, v2
	v_pk_mul_f32 v[84:85], v[24:25], v[70:71] op_sel_hi:[1,0]
	v_pk_mul_f32 v[82:83], v[26:27], v[70:71] op_sel_hi:[1,0]
	v_add_f32_e32 v2, v84, v2
	v_add_f32_e32 v2, v85, v2
	v_add_f32_e32 v2, v82, v2
	v_add_f32_e32 v2, v83, v2
	v_pk_mul_f32 v[84:85], v[28:29], v[70:71] op_sel_hi:[1,0]
	v_pk_mul_f32 v[82:83], v[30:31], v[70:71] op_sel_hi:[1,0]
	v_add_f32_e32 v2, v84, v2
	v_add_f32_e32 v2, v85, v2
	v_add_f32_e32 v2, v82, v2
	v_add_f32_e32 v2, v83, v2
	v_pk_mul_f32 v[84:85], v[32:33], v[70:71] op_sel_hi:[1,0]
	v_pk_mul_f32 v[82:83], v[34:35], v[70:71] op_sel_hi:[1,0]
	v_add_f32_e32 v2, v84, v2
	v_add_f32_e32 v2, v85, v2
	v_add_f32_e32 v2, v82, v2
	v_add_f32_e32 v2, v83, v2
	v_pk_mul_f32 v[84:85], v[36:37], v[70:71] op_sel_hi:[1,0]
	v_pk_mul_f32 v[82:83], v[38:39], v[70:71] op_sel_hi:[1,0]
	v_add_f32_e32 v2, v84, v2
	v_add_f32_e32 v2, v85, v2
	v_add_f32_e32 v2, v82, v2
	v_add_f32_e32 v2, v83, v2
	v_pk_mul_f32 v[84:85], v[40:41], v[70:71] op_sel_hi:[1,0]
	v_pk_mul_f32 v[82:83], v[42:43], v[70:71] op_sel_hi:[1,0]
	v_add_f32_e32 v2, v84, v2
	v_add_f32_e32 v2, v85, v2
	v_add_f32_e32 v2, v82, v2
	v_add_f32_e32 v2, v83, v2
	v_pk_mul_f32 v[84:85], v[44:45], v[70:71] op_sel_hi:[1,0]
	v_pk_mul_f32 v[82:83], v[46:47], v[70:71] op_sel_hi:[1,0]
	v_add_f32_e32 v2, v84, v2
	v_add_f32_e32 v2, v85, v2
	v_add_f32_e32 v2, v82, v2
	v_add_f32_e32 v2, v83, v2
	v_pk_mul_f32 v[84:85], v[48:49], v[70:71] op_sel_hi:[1,0]
	v_pk_mul_f32 v[82:83], v[50:51], v[70:71] op_sel_hi:[1,0]
	v_add_f32_e32 v2, v84, v2
	v_add_f32_e32 v2, v85, v2
	v_add_f32_e32 v2, v82, v2
	v_add_f32_e32 v2, v83, v2
	v_pk_mul_f32 v[84:85], v[52:53], v[70:71] op_sel_hi:[1,0]
	v_pk_mul_f32 v[82:83], v[54:55], v[70:71] op_sel_hi:[1,0]
	v_add_f32_e32 v2, v84, v2
	v_add_f32_e32 v2, v85, v2
	v_add_f32_e32 v2, v82, v2
	v_add_f32_e32 v2, v83, v2
	v_pk_mul_f32 v[82:83], v[56:57], v[70:71] op_sel_hi:[1,0]
	v_readlane_b32 s48, v253, 55
	v_add_f32_e32 v2, v82, v2
	v_add_f32_e32 v2, v83, v2
	v_add_f32_e32 v2, v68, v2
	v_add_f32_e32 v2, v69, v2
	v_add_f32_e32 v2, v72, v2
	v_add_f32_e32 v2, v73, v2
	v_add_f32_e32 v2, v74, v2
	v_add_f32_e32 v2, v75, v2
	v_add_f32_e32 v2, v76, v2
	v_add_f32_e32 v2, v77, v2
	v_add_f32_e32 v2, v78, v2
	v_add_f32_e32 v72, v79, v2
	ds_bpermute_b32 v73, v91, v72
	v_lshlrev_b32_e32 v2, 1, v166
	v_lshl_add_u64 v[68:69], v[80:81], 0, v[2:3]
	v_readlane_b32 s56, v253, 63
	v_readlane_b32 s57, v254, 0
	s_waitcnt lgkmcnt(0)
; DI f32x4 ld4bf(const bf16_t* p) { const u32x2 w = *(const u32x2*)p; f32x4 o; o.x = bf2f(w.x & 0xffffu); o.y = bf2f(w.x >> 16); o.z = bf2f(w.y & 0xffffu); o.w = bf2f(w.y >> 16); return o; }
; DI void mlstm_unit(const Args& a, LAS unsigned char* lds, int b, int h, int J) {
;     ...
;     const float mu = s1 * (1.f / 128.f);
;     float s2 = 0.f;
; #pragma unroll
;     for (int db = 0; db < 4; ++db)
; #pragma unroll
;         for (int reg = 0; reg < 16; ++reg) { const float dlt = O[db][reg] - mu; s2 += dlt * dlt; }
;     s2 += __shfl_xor(s2, 32);
;     const float rstd = 1.f / sqrtf(s2 * (1.f / 128.f) + EPS);
;     const float* gn = INF(a, I_GNORM) + h * 128; const bf16_t* ob = (const bf16_t*)(ws + WS_OB) + row * 512 + h * 128; bf16_t* op = (bf16_t*)(ws + WS_OAHB) + row * 1024 + 512 + h * 128;
; #pragma unroll
;     for (int db = 0; db < 4; ++db)
; #pragma unroll
;         for (int rg = 0; rg < 4; ++rg) { const int dv = 32 * db + 8 * rg + 4 * h2; const f32x4 g4 = *(const f32x4*)(gn + dv), o4 = ld4bf(ob + dv);
	v_add_f32_e32 v72, v72, v73
	v_mul_f32_e32 v90, 0x3c000000, v72
	v_pk_fma_f32 v[92:93], v[4:5], v[70:71], v[90:91] op_sel_hi:[1,0,0] neg_lo:[0,0,1] neg_hi:[0,0,1]
	v_pk_fma_f32 v[96:97], v[6:7], v[70:71], v[90:91] op_sel_hi:[1,0,0] neg_lo:[0,0,1] neg_hi:[0,0,1]
	v_pk_mul_f32 v[94:95], v[92:93], v[92:93]
	v_pk_mul_f32 v[98:99], v[96:97], v[96:97]
	v_pk_fma_f32 v[100:101], v[8:9], v[70:71], v[90:91] op_sel_hi:[1,0,0] neg_lo:[0,0,1] neg_hi:[0,0,1]
	v_pk_fma_f32 v[104:105], v[10:11], v[70:71], v[90:91] op_sel_hi:[1,0,0] neg_lo:[0,0,1] neg_hi:[0,0,1]
	v_pk_fma_f32 v[108:109], v[12:13], v[70:71], v[90:91] op_sel_hi:[1,0,0] neg_lo:[0,0,1] neg_hi:[0,0,1]
	v_pk_fma_f32 v[112:113], v[14:15], v[70:71], v[90:91] op_sel_hi:[1,0,0] neg_lo:[0,0,1] neg_hi:[0,0,1]
	v_pk_fma_f32 v[116:117], v[16:17], v[70:71], v[90:91] op_sel_hi:[1,0,0] neg_lo:[0,0,1] neg_hi:[0,0,1]
	v_pk_fma_f32 v[120:121], v[18:19], v[70:71], v[90:91] op_sel_hi:[1,0,0] neg_lo:[0,0,1] neg_hi:[0,0,1]
	v_pk_fma_f32 v[124:125], v[20:21], v[70:71], v[90:91] op_sel_hi:[1,0,0] neg_lo:[0,0,1] neg_hi:[0,0,1]
	v_pk_fma_f32 v[126:127], v[22:23], v[70:71], v[90:91] op_sel_hi:[1,0,0] neg_lo:[0,0,1] neg_hi:[0,0,1]
	v_pk_fma_f32 v[82:83], v[24:25], v[70:71], v[90:91] op_sel_hi:[1,0,0] neg_lo:[0,0,1] neg_hi:[0,0,1]
	v_pk_fma_f32 v[80:81], v[26:27], v[70:71], v[90:91] op_sel_hi:[1,0,0] neg_lo:[0,0,1] neg_hi:[0,0,1]
	v_pk_fma_f32 v[78:79], v[28:29], v[70:71], v[90:91] op_sel_hi:[1,0,0] neg_lo:[0,0,1] neg_hi:[0,0,1]
	v_pk_fma_f32 v[76:77], v[30:31], v[70:71], v[90:91] op_sel_hi:[1,0,0] neg_lo:[0,0,1] neg_hi:[0,0,1]
	v_pk_fma_f32 v[74:75], v[32:33], v[70:71], v[90:91] op_sel_hi:[1,0,0] neg_lo:[0,0,1] neg_hi:[0,0,1]
	v_pk_fma_f32 v[72:73], v[34:35], v[70:71], v[90:91] op_sel_hi:[1,0,0] neg_lo:[0,0,1] neg_hi:[0,0,1]
	v_pk_fma_f32 v[34:35], v[36:37], v[70:71], v[90:91] op_sel_hi:[1,0,0] neg_lo:[0,0,1] neg_hi:[0,0,1]
	v_pk_fma_f32 v[36:37], v[38:39], v[70:71], v[90:91] op_sel_hi:[1,0,0] neg_lo:[0,0,1] neg_hi:[0,0,1]
	v_pk_fma_f32 v[30:31], v[40:41], v[70:71], v[90:91] op_sel_hi:[1,0,0] neg_lo:[0,0,1] neg_hi:[0,0,1]
	v_pk_fma_f32 v[32:33], v[42:43], v[70:71], v[90:91] op_sel_hi:[1,0,0] neg_lo:[0,0,1] neg_hi:[0,0,1]
	v_pk_fma_f32 v[26:27], v[44:45], v[70:71], v[90:91] op_sel_hi:[1,0,0] neg_lo:[0,0,1] neg_hi:[0,0,1]
	v_pk_fma_f32 v[28:29], v[46:47], v[70:71], v[90:91] op_sel_hi:[1,0,0] neg_lo:[0,0,1] neg_hi:[0,0,1]
	v_pk_fma_f32 v[22:23], v[48:49], v[70:71], v[90:91] op_sel_hi:[1,0,0] neg_lo:[0,0,1] neg_hi:[0,0,1]
	v_pk_fma_f32 v[24:25], v[50:51], v[70:71], v[90:91] op_sel_hi:[1,0,0] neg_lo:[0,0,1] neg_hi:[0,0,1]
	v_pk_fma_f32 v[16:17], v[52:53], v[70:71], v[90:91] op_sel_hi:[1,0,0] neg_lo:[0,0,1] neg_hi:[0,0,1]
	v_pk_fma_f32 v[18:19], v[54:55], v[70:71], v[90:91] op_sel_hi:[1,0,0] neg_lo:[0,0,1] neg_hi:[0,0,1]
	v_pk_fma_f32 v[12:13], v[56:57], v[70:71], v[90:91] op_sel_hi:[1,0,0] neg_lo:[0,0,1] neg_hi:[0,0,1]
	v_pk_fma_f32 v[8:9], v[62:63], v[70:71], v[90:91] op_sel_hi:[1,0,0] neg_lo:[0,0,1] neg_hi:[0,0,1]
	v_pk_fma_f32 v[6:7], v[64:65], v[70:71], v[90:91] op_sel_hi:[1,0,0] neg_lo:[0,0,1] neg_hi:[0,0,1]
	v_pk_fma_f32 v[4:5], v[66:67], v[70:71], v[90:91] op_sel_hi:[1,0,0] neg_lo:[0,0,1] neg_hi:[0,0,1]
	v_pk_fma_f32 v[14:15], v[58:59], v[70:71], v[90:91] op_sel_hi:[1,0,0] neg_lo:[0,0,1] neg_hi:[0,0,1]
	v_pk_fma_f32 v[10:11], v[60:61], v[70:71], v[90:91] op_sel_hi:[1,0,0] neg_lo:[0,0,1] neg_hi:[0,0,1]
	v_add_f32_e32 v70, v94, v95
	v_add_f32_e32 v70, v98, v70
	v_pk_mul_f32 v[102:103], v[100:101], v[100:101]
	v_add_f32_e32 v70, v99, v70
	v_add_f32_e32 v70, v102, v70
	v_pk_mul_f32 v[106:107], v[104:105], v[104:105]
	v_add_f32_e32 v70, v103, v70
	v_add_f32_e32 v70, v106, v70
	v_pk_mul_f32 v[110:111], v[108:109], v[108:109]
	v_add_f32_e32 v70, v107, v70
	v_add_f32_e32 v70, v110, v70
	v_pk_mul_f32 v[114:115], v[112:113], v[112:113]
	v_add_f32_e32 v70, v111, v70
	v_add_f32_e32 v70, v114, v70
	v_pk_mul_f32 v[118:119], v[116:117], v[116:117]
	v_add_f32_e32 v70, v115, v70
	v_add_f32_e32 v70, v118, v70
	v_pk_mul_f32 v[122:123], v[120:121], v[120:121]
	v_add_f32_e32 v70, v119, v70
	v_add_f32_e32 v70, v122, v70
	v_pk_mul_f32 v[20:21], v[124:125], v[124:125]
	v_add_f32_e32 v70, v123, v70
	v_add_f32_e32 v20, v20, v70
	s_mov_b64 s[20:21], s[56:57]
	v_pk_mul_f32 v[128:129], v[126:127], v[126:127]
	v_add_f32_e32 v20, v21, v20
	s_add_u32 s0, s20, s0
	v_add_f32_e32 v20, v128, v20
	s_addc_u32 s1, s21, 0
	v_pk_mul_f32 v[130:131], v[82:83], v[82:83]
	v_add_f32_e32 v20, v129, v20
	global_load_dwordx4 v[84:87], v71, s[0:1]
	global_load_dwordx2 v[88:89], v[68:69], off
	v_add_f32_e32 v20, v130, v20
	s_waitcnt vmcnt(5)
	v_pk_mul_f32 v[132:133], v[80:81], v[80:81]
	v_add_f32_e32 v20, v131, v20
	v_add_f32_e32 v20, v132, v20
	v_pk_mul_f32 v[134:135], v[78:79], v[78:79]
	v_add_f32_e32 v20, v133, v20
	v_add_f32_e32 v20, v134, v20
	s_waitcnt vmcnt(4)
	v_pk_mul_f32 v[136:137], v[76:77], v[76:77]
	v_add_f32_e32 v20, v135, v20
	v_add_f32_e32 v20, v136, v20
	v_pk_mul_f32 v[138:139], v[74:75], v[74:75]
	v_add_f32_e32 v20, v137, v20
	v_add_f32_e32 v20, v138, v20
	s_waitcnt vmcnt(3)
; DI unsigned pk2(float lo, float hi) { f32x2 v = {lo, hi}; bf16x2_t b = __builtin_convertvector(v, bf16x2_t); return __builtin_bit_cast(unsigned, b); }
; DI f32x4 ld4bf(const bf16_t* p) { const u32x2 w = *(const u32x2*)p; f32x4 o; o.x = bf2f(w.x & 0xffffu); o.y = bf2f(w.x >> 16); o.z = bf2f(w.y & 0xffffu); o.w = bf2f(w.y >> 16); return o; }
; DI void mlstm_unit(const Args& a, LAS unsigned char* lds, int b, int h, int J) {
;     ...
;     const float rstd = 1.f / sqrtf(s2 * (1.f / 128.f) + EPS);
;     const float* gn = INF(a, I_GNORM) + h * 128; const bf16_t* ob = (const bf16_t*)(ws + WS_OB) + row * 512 + h * 128; bf16_t* op = (bf16_t*)(ws + WS_OAHB) + row * 1024 + 512 + h * 128;
; #pragma unroll
;     for (int db = 0; db < 4; ++db)
; #pragma unroll
;         for (int rg = 0; rg < 4; ++rg) { const int dv = 32 * db + 8 * rg + 4 * h2; const f32x4 g4 = *(const f32x4*)(gn + dv), o4 = ld4bf(ob + dv);
;             u32x2 w; w.x = pk2((O[db][4 * rg] - mu) * rstd * g4.x * o4.x, (O[db][4 * rg + 1] - mu) * rstd * g4.y * o4.y);
;             w.y = pk2((O[db][4 * rg + 2] - mu) * rstd * g4.z * o4.z, (O[db][4 * rg + 3] - mu) * rstd * g4.w * o4.w); *(u32x2*)(op + dv) = w; }
	v_pk_mul_f32 v[140:141], v[72:73], v[72:73]
	v_add_f32_e32 v20, v139, v20
	v_add_f32_e32 v20, v140, v20
	v_pk_mul_f32 v[142:143], v[34:35], v[34:35]
	v_add_f32_e32 v20, v141, v20
	v_add_f32_e32 v20, v142, v20
	v_pk_mul_f32 v[38:39], v[36:37], v[36:37]
	v_add_f32_e32 v20, v143, v20
	v_add_f32_e32 v20, v38, v20
	v_pk_mul_f32 v[40:41], v[30:31], v[30:31]
	v_add_f32_e32 v20, v39, v20
	v_add_f32_e32 v20, v40, v20
	v_pk_mul_f32 v[42:43], v[32:33], v[32:33]
	v_add_f32_e32 v20, v41, v20
	v_add_f32_e32 v20, v42, v20
	v_pk_mul_f32 v[44:45], v[26:27], v[26:27]
	v_add_f32_e32 v20, v43, v20
	v_add_f32_e32 v20, v44, v20
	v_pk_mul_f32 v[46:47], v[28:29], v[28:29]
	v_add_f32_e32 v20, v45, v20
	v_add_f32_e32 v20, v46, v20
	v_pk_mul_f32 v[48:49], v[22:23], v[22:23]
	v_add_f32_e32 v20, v47, v20
	v_add_f32_e32 v20, v48, v20
	v_pk_mul_f32 v[50:51], v[24:25], v[24:25]
	v_add_f32_e32 v20, v49, v20
	v_add_f32_e32 v20, v50, v20
	v_pk_mul_f32 v[52:53], v[16:17], v[16:17]
	v_add_f32_e32 v20, v51, v20
	v_add_f32_e32 v20, v52, v20
	v_pk_mul_f32 v[54:55], v[18:19], v[18:19]
	v_add_f32_e32 v20, v53, v20
	v_add_f32_e32 v20, v54, v20
	v_pk_mul_f32 v[56:57], v[12:13], v[12:13]
	v_add_f32_e32 v20, v55, v20
	v_add_f32_e32 v20, v56, v20
	v_pk_mul_f32 v[58:59], v[14:15], v[14:15]
	v_add_f32_e32 v20, v57, v20
	v_add_f32_e32 v20, v58, v20
	v_pk_mul_f32 v[60:61], v[10:11], v[10:11]
	v_add_f32_e32 v20, v59, v20
	v_add_f32_e32 v20, v60, v20
	v_pk_mul_f32 v[62:63], v[8:9], v[8:9]
	v_add_f32_e32 v20, v61, v20
	v_add_f32_e32 v20, v62, v20
	v_pk_mul_f32 v[64:65], v[6:7], v[6:7]
	v_add_f32_e32 v20, v63, v20
	v_add_f32_e32 v20, v64, v20
	v_pk_mul_f32 v[66:67], v[4:5], v[4:5]
	v_add_f32_e32 v20, v65, v20
	v_add_f32_e32 v20, v66, v20
	v_add_f32_e32 v38, v67, v20
	ds_bpermute_b32 v39, v91, v38
	v_lshlrev_b64 v[20:21], 11, v[152:153]
	v_lshl_add_u64 v[20:21], s[94:95], 0, v[20:21]
	v_lshl_add_u64 v[20:21], v[20:21], 0, s[16:17]
	v_lshl_add_u64 v[20:21], v[20:21], 0, v[2:3]
	s_waitcnt lgkmcnt(0)
	v_add_f32_e32 v38, v38, v39
	v_fmamk_f32 v38, v38, 0x3c000000, v164
	v_mul_f32_e32 v39, 0x4f800000, v38
	v_cmp_gt_f32_e32 vcc, s45, v38
	global_load_dwordx2 v[42:43], v[68:69], off offset:16
	global_load_dwordx2 v[44:45], v[68:69], off offset:32
	global_load_dwordx2 v[46:47], v[68:69], off offset:48
	global_load_dwordx4 v[128:131], v71, s[0:1] offset:32
	global_load_dwordx4 v[132:135], v71, s[0:1] offset:64
	global_load_dwordx4 v[136:139], v71, s[0:1] offset:96
	global_load_dwordx4 v[140:143], v71, s[0:1] offset:128
	global_load_dwordx2 v[94:95], v[68:69], off offset:64
	global_load_dwordx4 v[144:147], v71, s[0:1] offset:160
	global_load_dwordx2 v[98:99], v[68:69], off offset:80
	global_load_dwordx4 v[148:151], v71, s[0:1] offset:192
	global_load_dwordx2 v[102:103], v[68:69], off offset:96
	global_load_dwordx4 v[152:155], v71, s[0:1] offset:224
	global_load_dwordx2 v[106:107], v[68:69], off offset:112
	global_load_dwordx4 v[200:203], v71, s[0:1] offset:256
	global_load_dwordx2 v[110:111], v[68:69], off offset:128
	global_load_dwordx4 v[204:207], v71, s[0:1] offset:288
	global_load_dwordx2 v[114:115], v[68:69], off offset:144
	global_load_dwordx4 v[208:211], v71, s[0:1] offset:320
	global_load_dwordx2 v[118:119], v[68:69], off offset:160
	global_load_dwordx4 v[212:215], v71, s[0:1] offset:352
	global_load_dwordx2 v[122:123], v[68:69], off offset:176
	global_load_dwordx4 v[220:223], v71, s[0:1] offset:384
	global_load_dwordx2 v[156:157], v[68:69], off offset:192
	global_load_dwordx4 v[224:227], v71, s[0:1] offset:416
	global_load_dwordx2 v[216:217], v[68:69], off offset:208
	global_load_dwordx4 v[228:231], v71, s[0:1] offset:448
	global_load_dwordx2 v[232:233], v[68:69], off offset:224
	global_load_dwordx4 v[236:239], v71, s[0:1] offset:480
	global_load_dwordx2 v[240:241], v[68:69], off offset:240
	v_cndmask_b32_e32 v40, v38, v39, vcc
	v_sqrt_f32_e32 v41, v40
	v_readlane_b32 s49, v253, 56
	v_readlane_b32 s50, v253, 57
	s_waitcnt vmcnt(30)
	v_lshlrev_b32_e32 v38, 16, v89
	v_add_u32_e32 v48, -1, v41
	v_fma_f32 v49, -v48, v41, v40
	v_cmp_ge_f32_e64 s[2:3], 0, v49
	v_add_u32_e32 v49, 1, v41
	v_and_b32_e32 v39, 0xffff0000, v89
	v_cndmask_b32_e64 v48, v41, v48, s[2:3]
	v_fma_f32 v41, -v49, v41, v40
	v_cmp_lt_f32_e64 s[2:3], 0, v41
	v_readlane_b32 s51, v253, 58
	v_readlane_b32 s52, v253, 59
	v_cndmask_b32_e64 v41, v48, v49, s[2:3]
	v_mul_f32_e32 v48, 0x37800000, v41
	v_cndmask_b32_e32 v41, v41, v48, vcc
	v_cmp_class_f32_e32 vcc, v40, v165
	v_readlane_b32 s53, v253, 60
	v_readlane_b32 s54, v253, 61
	v_cndmask_b32_e32 v48, v41, v40, vcc
	v_div_scale_f32 v49, s[2:3], v48, v48, 1.0
	v_rcp_f32_e32 v50, v49
	v_lshlrev_b32_e32 v40, 16, v88
	v_and_b32_e32 v41, 0xffff0000, v88
	v_readlane_b32 s55, v253, 62
	v_fma_f32 v2, -v49, v50, 1.0
	v_fmac_f32_e32 v50, v2, v50
	v_div_scale_f32 v2, vcc, 1.0, v48, 1.0
	v_mul_f32_e32 v51, v2, v50
	v_fma_f32 v52, -v49, v51, v2
	v_fmac_f32_e32 v51, v52, v50
	v_fma_f32 v2, -v49, v51, v2
	v_div_fmas_f32 v2, v2, v50, v51
	v_div_fixup_f32 v2, v2, v48, 1.0
	v_readlane_b32 s58, v254, 1
	v_readlane_b32 s59, v254, 2
	v_readlane_b32 s60, v254, 3
	v_readlane_b32 s61, v254, 4
	v_readlane_b32 s62, v254, 5
	v_readlane_b32 s63, v254, 6
	v_pk_mul_f32 v[92:93], v[92:93], v[2:3] op_sel_hi:[1,0]
	v_pk_mul_f32 v[96:97], v[96:97], v[2:3] op_sel_hi:[1,0]
	v_pk_mul_f32 v[92:93], v[84:85], v[92:93]
	v_pk_mul_f32 v[96:97], v[86:87], v[96:97]
	s_nop 0
	v_pk_mul_f32 v[92:93], v[92:93], v[40:41]
	v_pk_mul_f32 v[96:97], v[96:97], v[38:39]
	s_nop 0
	v_cvt_pk_bf16_f32 v92, v92, v93
	v_cvt_pk_bf16_f32 v93, v96, v97
	s_waitcnt vmcnt(26)
; DI unsigned pk2(float lo, float hi) { f32x2 v = {lo, hi}; bf16x2_t b = __builtin_convertvector(v, bf16x2_t); return __builtin_bit_cast(unsigned, b); }
; DI f32x4 ld4bf(const bf16_t* p) { const u32x2 w = *(const u32x2*)p; f32x4 o; o.x = bf2f(w.x & 0xffffu); o.y = bf2f(w.x >> 16); o.z = bf2f(w.y & 0xffffu); o.w = bf2f(w.y >> 16); return o; }
; DI void mlstm_unit(const Args& a, LAS unsigned char* lds, int b, int h, int J) {
;     ...
;     for (int db = 0; db < 4; ++db)
; #pragma unroll
;         for (int rg = 0; rg < 4; ++rg) { const int dv = 32 * db + 8 * rg + 4 * h2; const f32x4 g4 = *(const f32x4*)(gn + dv), o4 = ld4bf(ob + dv);
;             u32x2 w; w.x = pk2((O[db][4 * rg] - mu) * rstd * g4.x * o4.x, (O[db][4 * rg + 1] - mu) * rstd * g4.y * o4.y);
;             w.y = pk2((O[db][4 * rg + 2] - mu) * rstd * g4.z * o4.z, (O[db][4 * rg + 3] - mu) * rstd * g4.w * o4.w); *(u32x2*)(op + dv) = w; }
	v_pk_mul_f32 v[100:101], v[100:101], v[2:3] op_sel_hi:[1,0]
	v_pk_mul_f32 v[104:105], v[104:105], v[2:3] op_sel_hi:[1,0]
	v_lshlrev_b32_e32 v52, 16, v42
	v_and_b32_e32 v53, 0xffff0000, v42
	v_lshlrev_b32_e32 v54, 16, v43
	v_and_b32_e32 v55, 0xffff0000, v43
	v_pk_mul_f32 v[100:101], v[128:129], v[100:101]
	v_pk_mul_f32 v[104:105], v[130:131], v[104:105]
	s_nop 0
	v_pk_mul_f32 v[100:101], v[100:101], v[52:53]
	v_pk_mul_f32 v[104:105], v[104:105], v[54:55]
	s_nop 0
	v_cvt_pk_bf16_f32 v100, v100, v101
	v_cvt_pk_bf16_f32 v101, v104, v105
	s_waitcnt vmcnt(25)
	v_pk_mul_f32 v[108:109], v[108:109], v[2:3] op_sel_hi:[1,0]
	v_pk_mul_f32 v[112:113], v[112:113], v[2:3] op_sel_hi:[1,0]
	v_lshlrev_b32_e32 v48, 16, v44
	v_and_b32_e32 v49, 0xffff0000, v44
	v_lshlrev_b32_e32 v50, 16, v45
	v_and_b32_e32 v51, 0xffff0000, v45
	v_pk_mul_f32 v[108:109], v[132:133], v[108:109]
	v_pk_mul_f32 v[112:113], v[134:135], v[112:113]
	s_nop 0
	v_pk_mul_f32 v[108:109], v[108:109], v[48:49]
	v_pk_mul_f32 v[112:113], v[112:113], v[50:51]
	s_nop 0
	v_cvt_pk_bf16_f32 v108, v108, v109
	v_cvt_pk_bf16_f32 v109, v112, v113
	s_waitcnt vmcnt(24)
	v_pk_mul_f32 v[116:117], v[116:117], v[2:3] op_sel_hi:[1,0]
	v_pk_mul_f32 v[120:121], v[120:121], v[2:3] op_sel_hi:[1,0]
	v_lshlrev_b32_e32 v52, 16, v46
	v_and_b32_e32 v53, 0xffff0000, v46
	v_lshlrev_b32_e32 v54, 16, v47
	v_and_b32_e32 v55, 0xffff0000, v47
	v_pk_mul_f32 v[116:117], v[136:137], v[116:117]
	v_pk_mul_f32 v[120:121], v[138:139], v[120:121]
	s_nop 0
	v_pk_mul_f32 v[116:117], v[116:117], v[52:53]
	v_pk_mul_f32 v[120:121], v[120:121], v[54:55]
	s_nop 0
	v_cvt_pk_bf16_f32 v116, v116, v117
	v_cvt_pk_bf16_f32 v117, v120, v121
	s_waitcnt vmcnt(22)
	v_pk_mul_f32 v[124:125], v[124:125], v[2:3] op_sel_hi:[1,0]
	v_pk_mul_f32 v[126:127], v[126:127], v[2:3] op_sel_hi:[1,0]
	v_lshlrev_b32_e32 v48, 16, v94
	v_and_b32_e32 v49, 0xffff0000, v94
	v_lshlrev_b32_e32 v50, 16, v95
	v_and_b32_e32 v51, 0xffff0000, v95
	v_pk_mul_f32 v[124:125], v[140:141], v[124:125]
	v_pk_mul_f32 v[126:127], v[142:143], v[126:127]
	s_nop 0
	v_pk_mul_f32 v[124:125], v[124:125], v[48:49]
	v_pk_mul_f32 v[126:127], v[126:127], v[50:51]
	s_nop 0
	v_cvt_pk_bf16_f32 v124, v124, v125
	v_cvt_pk_bf16_f32 v125, v126, v127
	s_waitcnt vmcnt(20)
	v_pk_mul_f32 v[82:83], v[82:83], v[2:3] op_sel_hi:[1,0]
	v_pk_mul_f32 v[80:81], v[80:81], v[2:3] op_sel_hi:[1,0]
	v_lshlrev_b32_e32 v52, 16, v98
	v_and_b32_e32 v53, 0xffff0000, v98
	v_lshlrev_b32_e32 v54, 16, v99
	v_and_b32_e32 v55, 0xffff0000, v99
	v_pk_mul_f32 v[82:83], v[144:145], v[82:83]
	v_pk_mul_f32 v[80:81], v[146:147], v[80:81]
	s_nop 0
	v_pk_mul_f32 v[82:83], v[82:83], v[52:53]
	v_pk_mul_f32 v[80:81], v[80:81], v[54:55]
	s_nop 0
	v_cvt_pk_bf16_f32 v82, v82, v83
	v_cvt_pk_bf16_f32 v83, v80, v81
	s_waitcnt vmcnt(18)
	v_pk_mul_f32 v[78:79], v[78:79], v[2:3] op_sel_hi:[1,0]
	v_pk_mul_f32 v[76:77], v[76:77], v[2:3] op_sel_hi:[1,0]
	v_lshlrev_b32_e32 v48, 16, v102
	v_and_b32_e32 v49, 0xffff0000, v102
	v_lshlrev_b32_e32 v50, 16, v103
	v_and_b32_e32 v51, 0xffff0000, v103
	v_pk_mul_f32 v[78:79], v[148:149], v[78:79]
	v_pk_mul_f32 v[76:77], v[150:151], v[76:77]
	s_nop 0
	v_pk_mul_f32 v[78:79], v[78:79], v[48:49]
	v_pk_mul_f32 v[76:77], v[76:77], v[50:51]
	s_nop 0
	v_cvt_pk_bf16_f32 v78, v78, v79
	v_cvt_pk_bf16_f32 v79, v76, v77
	s_waitcnt vmcnt(16)
	v_pk_mul_f32 v[74:75], v[74:75], v[2:3] op_sel_hi:[1,0]
	v_pk_mul_f32 v[72:73], v[72:73], v[2:3] op_sel_hi:[1,0]
	v_lshlrev_b32_e32 v52, 16, v106
	v_and_b32_e32 v53, 0xffff0000, v106
	v_lshlrev_b32_e32 v54, 16, v107
	v_and_b32_e32 v55, 0xffff0000, v107
	v_pk_mul_f32 v[74:75], v[152:153], v[74:75]
	v_pk_mul_f32 v[72:73], v[154:155], v[72:73]
	s_nop 0
	v_pk_mul_f32 v[74:75], v[74:75], v[52:53]
	v_pk_mul_f32 v[72:73], v[72:73], v[54:55]
	s_nop 0
	v_cvt_pk_bf16_f32 v74, v74, v75
	v_cvt_pk_bf16_f32 v75, v72, v73
	s_waitcnt vmcnt(14)
	v_pk_mul_f32 v[34:35], v[34:35], v[2:3] op_sel_hi:[1,0]
	v_pk_mul_f32 v[36:37], v[36:37], v[2:3] op_sel_hi:[1,0]
	v_lshlrev_b32_e32 v48, 16, v110
	v_and_b32_e32 v49, 0xffff0000, v110
	v_lshlrev_b32_e32 v50, 16, v111
	v_and_b32_e32 v51, 0xffff0000, v111
	v_pk_mul_f32 v[34:35], v[200:201], v[34:35]
	v_pk_mul_f32 v[36:37], v[202:203], v[36:37]
	s_nop 0
	v_pk_mul_f32 v[34:35], v[34:35], v[48:49]
	v_pk_mul_f32 v[36:37], v[36:37], v[50:51]
	s_nop 0
	v_cvt_pk_bf16_f32 v34, v34, v35
	v_cvt_pk_bf16_f32 v35, v36, v37
	s_waitcnt vmcnt(12)
	v_pk_mul_f32 v[30:31], v[30:31], v[2:3] op_sel_hi:[1,0]
	v_pk_mul_f32 v[32:33], v[32:33], v[2:3] op_sel_hi:[1,0]
	v_lshlrev_b32_e32 v52, 16, v114
	v_and_b32_e32 v53, 0xffff0000, v114
	v_lshlrev_b32_e32 v54, 16, v115
	v_and_b32_e32 v55, 0xffff0000, v115
	v_pk_mul_f32 v[30:31], v[204:205], v[30:31]
	v_pk_mul_f32 v[32:33], v[206:207], v[32:33]
	s_nop 0
	v_pk_mul_f32 v[30:31], v[30:31], v[52:53]
	v_pk_mul_f32 v[32:33], v[32:33], v[54:55]
	s_nop 0
	v_cvt_pk_bf16_f32 v30, v30, v31
	v_cvt_pk_bf16_f32 v31, v32, v33
	s_waitcnt vmcnt(10)
; DI unsigned pk2(float lo, float hi) { f32x2 v = {lo, hi}; bf16x2_t b = __builtin_convertvector(v, bf16x2_t); return __builtin_bit_cast(unsigned, b); }
; DI f32x4 ld4bf(const bf16_t* p) { const u32x2 w = *(const u32x2*)p; f32x4 o; o.x = bf2f(w.x & 0xffffu); o.y = bf2f(w.x >> 16); o.z = bf2f(w.y & 0xffffu); o.w = bf2f(w.y >> 16); return o; }
; DI void mlstm_unit(const Args& a, LAS unsigned char* lds, int b, int h, int J) {
;     ...
;     for (int db = 0; db < 4; ++db)
; #pragma unroll
;         for (int rg = 0; rg < 4; ++rg) { const int dv = 32 * db + 8 * rg + 4 * h2; const f32x4 g4 = *(const f32x4*)(gn + dv), o4 = ld4bf(ob + dv);
;             u32x2 w; w.x = pk2((O[db][4 * rg] - mu) * rstd * g4.x * o4.x, (O[db][4 * rg + 1] - mu) * rstd * g4.y * o4.y);
;             w.y = pk2((O[db][4 * rg + 2] - mu) * rstd * g4.z * o4.z, (O[db][4 * rg + 3] - mu) * rstd * g4.w * o4.w); *(u32x2*)(op + dv) = w; }
;     __syncthreads();
	v_pk_mul_f32 v[26:27], v[26:27], v[2:3] op_sel_hi:[1,0]
	v_pk_mul_f32 v[28:29], v[28:29], v[2:3] op_sel_hi:[1,0]
	v_lshlrev_b32_e32 v48, 16, v118
	v_and_b32_e32 v49, 0xffff0000, v118
	v_lshlrev_b32_e32 v50, 16, v119
	v_and_b32_e32 v51, 0xffff0000, v119
	v_pk_mul_f32 v[26:27], v[208:209], v[26:27]
	v_pk_mul_f32 v[28:29], v[210:211], v[28:29]
	s_nop 0
	v_pk_mul_f32 v[26:27], v[26:27], v[48:49]
	v_pk_mul_f32 v[28:29], v[28:29], v[50:51]
	s_nop 0
	v_cvt_pk_bf16_f32 v26, v26, v27
	v_cvt_pk_bf16_f32 v27, v28, v29
	s_waitcnt vmcnt(8)
	v_pk_mul_f32 v[22:23], v[22:23], v[2:3] op_sel_hi:[1,0]
	v_pk_mul_f32 v[24:25], v[24:25], v[2:3] op_sel_hi:[1,0]
	v_lshlrev_b32_e32 v52, 16, v122
	v_and_b32_e32 v53, 0xffff0000, v122
	v_lshlrev_b32_e32 v54, 16, v123
	v_and_b32_e32 v55, 0xffff0000, v123
	v_pk_mul_f32 v[22:23], v[212:213], v[22:23]
	v_pk_mul_f32 v[24:25], v[214:215], v[24:25]
	s_nop 0
	v_pk_mul_f32 v[22:23], v[22:23], v[52:53]
	v_pk_mul_f32 v[24:25], v[24:25], v[54:55]
	s_nop 0
	v_cvt_pk_bf16_f32 v22, v22, v23
	v_cvt_pk_bf16_f32 v23, v24, v25
	s_waitcnt vmcnt(6)
	v_pk_mul_f32 v[16:17], v[16:17], v[2:3] op_sel_hi:[1,0]
	v_pk_mul_f32 v[18:19], v[18:19], v[2:3] op_sel_hi:[1,0]
	v_lshlrev_b32_e32 v48, 16, v156
	v_and_b32_e32 v49, 0xffff0000, v156
	v_lshlrev_b32_e32 v50, 16, v157
	v_and_b32_e32 v51, 0xffff0000, v157
	v_pk_mul_f32 v[16:17], v[220:221], v[16:17]
	v_pk_mul_f32 v[18:19], v[222:223], v[18:19]
	s_nop 0
	v_pk_mul_f32 v[16:17], v[16:17], v[48:49]
	v_pk_mul_f32 v[18:19], v[18:19], v[50:51]
	s_nop 0
	v_cvt_pk_bf16_f32 v16, v16, v17
	v_cvt_pk_bf16_f32 v17, v18, v19
	s_waitcnt vmcnt(4)
	v_pk_mul_f32 v[12:13], v[12:13], v[2:3] op_sel_hi:[1,0]
	v_pk_mul_f32 v[14:15], v[14:15], v[2:3] op_sel_hi:[1,0]
	v_lshlrev_b32_e32 v52, 16, v216
	v_and_b32_e32 v53, 0xffff0000, v216
	v_lshlrev_b32_e32 v54, 16, v217
	v_and_b32_e32 v55, 0xffff0000, v217
	v_pk_mul_f32 v[12:13], v[224:225], v[12:13]
	v_pk_mul_f32 v[14:15], v[226:227], v[14:15]
	s_nop 0
	v_pk_mul_f32 v[12:13], v[12:13], v[52:53]
	v_pk_mul_f32 v[14:15], v[14:15], v[54:55]
	s_nop 0
	v_cvt_pk_bf16_f32 v12, v12, v13
	v_cvt_pk_bf16_f32 v13, v14, v15
	s_waitcnt vmcnt(2)
	v_pk_mul_f32 v[10:11], v[10:11], v[2:3] op_sel_hi:[1,0]
	v_pk_mul_f32 v[8:9], v[8:9], v[2:3] op_sel_hi:[1,0]
	v_lshlrev_b32_e32 v48, 16, v232
	v_and_b32_e32 v49, 0xffff0000, v232
	v_lshlrev_b32_e32 v50, 16, v233
	v_and_b32_e32 v51, 0xffff0000, v233
	v_pk_mul_f32 v[10:11], v[228:229], v[10:11]
	v_pk_mul_f32 v[8:9], v[230:231], v[8:9]
	s_nop 0
	v_pk_mul_f32 v[10:11], v[10:11], v[48:49]
	v_pk_mul_f32 v[8:9], v[8:9], v[50:51]
	s_nop 0
	v_cvt_pk_bf16_f32 v10, v10, v11
	v_cvt_pk_bf16_f32 v11, v8, v9
	s_waitcnt vmcnt(0)
	v_pk_mul_f32 v[6:7], v[6:7], v[2:3] op_sel_hi:[1,0]
	v_pk_mul_f32 v[4:5], v[4:5], v[2:3] op_sel_hi:[1,0]
	v_lshlrev_b32_e32 v52, 16, v240
	v_and_b32_e32 v53, 0xffff0000, v240
	v_lshlrev_b32_e32 v54, 16, v241
	v_and_b32_e32 v55, 0xffff0000, v241
	v_pk_mul_f32 v[6:7], v[236:237], v[6:7]
	v_pk_mul_f32 v[4:5], v[238:239], v[4:5]
	s_nop 0
	v_pk_mul_f32 v[6:7], v[6:7], v[52:53]
	v_pk_mul_f32 v[4:5], v[4:5], v[54:55]
	s_nop 0
	v_cvt_pk_bf16_f32 v6, v6, v7
	v_cvt_pk_bf16_f32 v7, v4, v5
	v_lshl_add_u64 v[20:21], v[20:21], 0, s[14:15]
	global_store_dwordx2 v[20:21], v[92:93], off
	global_store_dwordx2 v[20:21], v[100:101], off offset:16
	global_store_dwordx2 v[20:21], v[108:109], off offset:32
	global_store_dwordx2 v[20:21], v[116:117], off offset:48
	global_store_dwordx2 v[20:21], v[124:125], off offset:64
	global_store_dwordx2 v[20:21], v[82:83], off offset:80
	global_store_dwordx2 v[20:21], v[78:79], off offset:96
	global_store_dwordx2 v[20:21], v[74:75], off offset:112
	global_store_dwordx2 v[20:21], v[34:35], off offset:128
	global_store_dwordx2 v[20:21], v[30:31], off offset:144
	global_store_dwordx2 v[20:21], v[26:27], off offset:160
	global_store_dwordx2 v[20:21], v[22:23], off offset:176
	global_store_dwordx2 v[20:21], v[16:17], off offset:192
	global_store_dwordx2 v[20:21], v[12:13], off offset:208
	global_store_dwordx2 v[20:21], v[10:11], off offset:224
	global_store_dwordx2 v[20:21], v[6:7], off offset:240
	s_barrier
	s_barrier
	s_mov_b64 s[0:1], exec
	v_readlane_b32 s2, v254, 43
	v_readlane_b32 s3, v254, 44
	s_and_b64 s[2:3], s[0:1], s[2:3]
	s_mov_b64 exec, s[2:3]
	s_cbranch_execz .LBB0_2093
	s_mov_b64 s[16:17], exec
	v_mbcnt_lo_u32_b32 v2, s16, 0
	v_mbcnt_hi_u32_b32 v2, s17, v2
	v_cmp_eq_u32_e32 vcc, 0, v2
	s_and_saveexec_b64 s[2:3], vcc
	s_cbranch_execz .LBB0_2092
	s_bcnt1_i32_b64 s10, s[16:17]
	v_readlane_b32 s16, v254, 45
	v_mov_b32_e32 v4, s10
	v_readlane_b32 s17, v254, 46
	s_nop 4
	global_atomic_add v4, v3, v4, s[16:17] offset:256 sc0
	s_branch .LBB0_2092
